# hand-written RG-LRU gate epilogue (packed f32, batched transcendental ops, stores at the end), on top of v9
# speedup vs baseline: 1.0063x; 1.0063x over previous
; __device__ __forceinline__ unsigned cvt_pk_bf16(float lo, float hi) { unsigned r; asm volatile("v_cvt_pk_bf16_f32 %0, %1, %2" : "=v"(r) : "v"(lo), "v"(hi)); return r; }
; __device__ __forceinline__ float sigmoidf_(float x) { return 1.f / (1.f + __expf(-x)); }
; __device__ __forceinline__ f32x4 bf4lo(u32x4 r) { return (f32x4){__uint_as_float(r.x << 16), __uint_as_float(r.x & 0xffff0000u), __uint_as_float(r.y << 16), __uint_as_float(r.y & 0xffff0000u)}; }
; __device__ __forceinline__ f32x4 bf4hi(u32x4 r) { return (f32x4){__uint_as_float(r.z << 16), __uint_as_float(r.z & 0xffff0000u), __uint_as_float(r.w << 16), __uint_as_float(r.w & 0xffff0000u)}; }
;     __device__ __forceinline__ void operator()(const f32x4 (&acc)[2][2][4][2], const Unit& u, int wr, int wc, int fr, int fq) const {
;         const int row0 = u.pm * 256 + wr * 64 + fr; const int cb = u.pn * 128 + wc * 32 + 8 * fq;
;         const f32x4 sp0 = *(const f32x4*)(lam + cb), sp1 = *(const f32x4*)(lam + cb + 4), rb0 = *(const f32x4*)(rgb + cb), rb1 = *(const f32x4*)(rgb + cb + 4), ib0 = *(const f32x4*)(igb + cb), ib1 = *(const f32x4*)(igb + cb + 4);
; #pragma unroll
;         for (int ai = 0; ai < 2; ++ai) {
;             f32x4 ucv[4][2];
; #pragma unroll
;             for (int m = 0; m < 4; ++m) { const u32x4 raw = *(const u32x4*)(UCBp + (size_t)(row0 + ai * 128 + m * 16) * 512 + cb); ucv[m][0] = bf4lo(raw); ucv[m][1] = bf4hi(raw); }
; #pragma unroll
;             for (int m = 0; m < 4; ++m)
; #pragma unroll
;                 for (int n = 0; n < 2; ++n) { const size_t off = (size_t)(row0 + ai * 128 + m * 16) * 512 + cb + 4 * n;
;                     const f32x4 uv = ucv[m][n], sp = n ? sp1 : sp0, rb = n ? rb1 : rb0, ib = n ? ib1 : ib0; u32x4 pk;
; #pragma unroll
;                     for (int j = 0; j < 4; ++j) { const float r = sigmoidf_(acc[ai][0][m][n][j] + rb[j]), ig = sigmoidf_(acc[ai][1][m][n][j] + ib[j]);
;                         const float la = sp[j] * r; const float ae = __expf(la); const float om = 1.f - ae; pk[j] = cvt_pk_bf16(om, sqrtf(om * (1.f + ae)) * ig * uv[j]); }
;                     *(u32x4*)(AX + off) = pk; }
;             asm volatile("" ::: "memory"); }
.LBB0_559:
	v_lshl_or_b32 v243, s33, 7, v189
	v_lshl_add_u32 v240, s40, 8, v177
	v_lshlrev_b32_e32 v242, 11, v240
	v_lshlrev_b32_e32 v240, 10, v240
	v_lshl_add_u32 v240, v243, 1, v240
	v_lshl_add_u32 v242, v243, 2, v242
	v_lshlrev_b32_e32 v243, 2, v243
	s_mov_b64 s[98:99], s[4:5]
	s_mov_b64 s[100:101], s[12:13]
	global_load_dwordx4 v[196:199], v243, s[10:11]
	global_load_dwordx4 v[200:203], v243, s[10:11] offset:16
	global_load_dwordx4 v[204:207], v243, s[18:19]
	global_load_dwordx4 v[208:211], v243, s[18:19] offset:16
	global_load_dwordx4 v[212:215], v243, s[22:23]
	global_load_dwordx4 v[216:219], v243, s[22:23] offset:16
	global_load_dwordx4 v[244:247], v240, s[98:99]
	v_mov_b32_e32 v194, 1.0
	v_mov_b32_e32 v222, 0xbfb8aa3b
	s_waitcnt vmcnt(1)
	v_mul_f32_e32 v196, 0x3fb8aa3b, v196
	v_mul_f32_e32 v197, 0x3fb8aa3b, v197
	v_mul_f32_e32 v198, 0x3fb8aa3b, v198
	v_mul_f32_e32 v199, 0x3fb8aa3b, v199
	v_mul_f32_e32 v200, 0x3fb8aa3b, v200
	v_mul_f32_e32 v201, 0x3fb8aa3b, v201
	v_mul_f32_e32 v202, 0x3fb8aa3b, v202
	v_mul_f32_e32 v203, 0x3fb8aa3b, v203
	v_mul_f32_e32 v204, 0xbfb8aa3b, v204
	v_mul_f32_e32 v205, 0xbfb8aa3b, v205
	v_mul_f32_e32 v206, 0xbfb8aa3b, v206
	v_mul_f32_e32 v207, 0xbfb8aa3b, v207
	v_mul_f32_e32 v208, 0xbfb8aa3b, v208
	v_mul_f32_e32 v209, 0xbfb8aa3b, v209
	v_mul_f32_e32 v210, 0xbfb8aa3b, v210
	v_mul_f32_e32 v211, 0xbfb8aa3b, v211
	v_mul_f32_e32 v212, 0xbfb8aa3b, v212
	v_mul_f32_e32 v213, 0xbfb8aa3b, v213
	v_mul_f32_e32 v214, 0xbfb8aa3b, v214
	v_mul_f32_e32 v215, 0xbfb8aa3b, v215
	v_mul_f32_e32 v216, 0xbfb8aa3b, v216
	v_mul_f32_e32 v217, 0xbfb8aa3b, v217
	v_mul_f32_e32 v218, 0xbfb8aa3b, v218
	v_mul_f32_e32 v219, 0xbfb8aa3b, v219
	s_add_u32 s98, s98, 0x4000
	s_addc_u32 s99, s99, 0
	global_load_dwordx4 v[248:251], v240, s[98:99]
	v_pk_fma_f32 v[148:149], v[148:149], v[222:223], v[204:205] op_sel_hi:[1,0,1]
	v_pk_fma_f32 v[150:151], v[150:151], v[222:223], v[206:207] op_sel_hi:[1,0,1]
	v_pk_fma_f32 v[140:141], v[140:141], v[222:223], v[208:209] op_sel_hi:[1,0,1]
	v_pk_fma_f32 v[142:143], v[142:143], v[222:223], v[210:211] op_sel_hi:[1,0,1]
	v_pk_fma_f32 v[144:145], v[144:145], v[222:223], v[212:213] op_sel_hi:[1,0,1]
	v_pk_fma_f32 v[146:147], v[146:147], v[222:223], v[214:215] op_sel_hi:[1,0,1]
	v_pk_fma_f32 v[136:137], v[136:137], v[222:223], v[216:217] op_sel_hi:[1,0,1]
	v_pk_fma_f32 v[138:139], v[138:139], v[222:223], v[218:219] op_sel_hi:[1,0,1]
	v_exp_f32_e32 v148, v148
	v_exp_f32_e32 v149, v149
	v_exp_f32_e32 v150, v150
	v_exp_f32_e32 v151, v151
	v_exp_f32_e32 v140, v140
	v_exp_f32_e32 v141, v141
	v_exp_f32_e32 v142, v142
	v_exp_f32_e32 v143, v143
	v_exp_f32_e32 v144, v144
	v_exp_f32_e32 v145, v145
	v_exp_f32_e32 v146, v146
	v_exp_f32_e32 v147, v147
	v_exp_f32_e32 v136, v136
	v_exp_f32_e32 v137, v137
	v_exp_f32_e32 v138, v138
	v_exp_f32_e32 v139, v139
	v_pk_add_f32 v[148:149], v[148:149], v[194:195] op_sel_hi:[1,0]
	v_pk_add_f32 v[150:151], v[150:151], v[194:195] op_sel_hi:[1,0]
	v_pk_add_f32 v[140:141], v[140:141], v[194:195] op_sel_hi:[1,0]
	v_pk_add_f32 v[142:143], v[142:143], v[194:195] op_sel_hi:[1,0]
	v_pk_add_f32 v[144:145], v[144:145], v[194:195] op_sel_hi:[1,0]
	v_pk_add_f32 v[146:147], v[146:147], v[194:195] op_sel_hi:[1,0]
	v_pk_add_f32 v[136:137], v[136:137], v[194:195] op_sel_hi:[1,0]
	v_pk_add_f32 v[138:139], v[138:139], v[194:195] op_sel_hi:[1,0]
	v_rcp_f32_e32 v148, v148
	v_rcp_f32_e32 v149, v149
	v_rcp_f32_e32 v150, v150
	v_rcp_f32_e32 v151, v151
	v_rcp_f32_e32 v140, v140
	v_rcp_f32_e32 v141, v141
	v_rcp_f32_e32 v142, v142
	v_rcp_f32_e32 v143, v143
	v_rcp_f32_e32 v144, v144
	v_rcp_f32_e32 v145, v145
	v_rcp_f32_e32 v146, v146
	v_rcp_f32_e32 v147, v147
	v_rcp_f32_e32 v136, v136
	v_rcp_f32_e32 v137, v137
	v_rcp_f32_e32 v138, v138
	v_rcp_f32_e32 v139, v139
	v_pk_mul_f32 v[148:149], v[148:149], v[196:197]
	v_pk_mul_f32 v[150:151], v[150:151], v[198:199]
	v_pk_mul_f32 v[140:141], v[140:141], v[200:201]
	v_pk_mul_f32 v[142:143], v[142:143], v[202:203]
	v_exp_f32_e32 v148, v148
	v_exp_f32_e32 v149, v149
	v_exp_f32_e32 v150, v150
	v_exp_f32_e32 v151, v151
	v_exp_f32_e32 v140, v140
	v_exp_f32_e32 v141, v141
	v_exp_f32_e32 v142, v142
	v_exp_f32_e32 v143, v143
	s_waitcnt vmcnt(1)
	v_lshlrev_b32_e32 v232, 16, v244
	v_and_b32_e32 v233, 0xffff0000, v244
	v_lshlrev_b32_e32 v234, 16, v245
	v_and_b32_e32 v235, 0xffff0000, v245
	v_lshlrev_b32_e32 v236, 16, v246
	v_and_b32_e32 v237, 0xffff0000, v246
	v_lshlrev_b32_e32 v238, 16, v247
	v_and_b32_e32 v239, 0xffff0000, v247
	v_pk_fma_f32 v[224:225], v[148:149], v[148:149], v[194:195] op_sel_hi:[1,1,0] neg_lo:[1,0,0] neg_hi:[1,0,0]
	v_pk_fma_f32 v[226:227], v[150:151], v[150:151], v[194:195] op_sel_hi:[1,1,0] neg_lo:[1,0,0] neg_hi:[1,0,0]
	v_pk_fma_f32 v[228:229], v[140:141], v[140:141], v[194:195] op_sel_hi:[1,1,0] neg_lo:[1,0,0] neg_hi:[1,0,0]
	v_pk_fma_f32 v[230:231], v[142:143], v[142:143], v[194:195] op_sel_hi:[1,1,0] neg_lo:[1,0,0] neg_hi:[1,0,0]
	v_pk_add_f32 v[148:149], v[194:195], v[148:149] op_sel_hi:[0,1] neg_lo:[0,1] neg_hi:[0,1]
	v_pk_add_f32 v[150:151], v[194:195], v[150:151] op_sel_hi:[0,1] neg_lo:[0,1] neg_hi:[0,1]
	v_pk_add_f32 v[140:141], v[194:195], v[140:141] op_sel_hi:[0,1] neg_lo:[0,1] neg_hi:[0,1]
	v_pk_add_f32 v[142:143], v[194:195], v[142:143] op_sel_hi:[0,1] neg_lo:[0,1] neg_hi:[0,1]
	v_pk_mul_f32 v[144:145], v[144:145], v[232:233]
	v_pk_mul_f32 v[146:147], v[146:147], v[234:235]
	v_pk_mul_f32 v[136:137], v[136:137], v[236:237]
	v_pk_mul_f32 v[138:139], v[138:139], v[238:239]
	v_sqrt_f32_e32 v224, v224
	v_sqrt_f32_e32 v225, v225
	v_sqrt_f32_e32 v226, v226
	v_sqrt_f32_e32 v227, v227
	v_sqrt_f32_e32 v228, v228
	v_sqrt_f32_e32 v229, v229
	v_sqrt_f32_e32 v230, v230
; __device__ __forceinline__ unsigned cvt_pk_bf16(float lo, float hi) { unsigned r; asm volatile("v_cvt_pk_bf16_f32 %0, %1, %2" : "=v"(r) : "v"(lo), "v"(hi)); return r; }
; __device__ __forceinline__ float sigmoidf_(float x) { return 1.f / (1.f + __expf(-x)); }
; __device__ __forceinline__ f32x4 bf4lo(u32x4 r) { return (f32x4){__uint_as_float(r.x << 16), __uint_as_float(r.x & 0xffff0000u), __uint_as_float(r.y << 16), __uint_as_float(r.y & 0xffff0000u)}; }
; __device__ __forceinline__ f32x4 bf4hi(u32x4 r) { return (f32x4){__uint_as_float(r.z << 16), __uint_as_float(r.z & 0xffff0000u), __uint_as_float(r.w << 16), __uint_as_float(r.w & 0xffff0000u)}; }
;     __device__ __forceinline__ void operator()(const f32x4 (&acc)[2][2][4][2], const Unit& u, int wr, int wc, int fr, int fq) const {
;     ...
;             for (int m = 0; m < 4; ++m) { const u32x4 raw = *(const u32x4*)(UCBp + (size_t)(row0 + ai * 128 + m * 16) * 512 + cb); ucv[m][0] = bf4lo(raw); ucv[m][1] = bf4hi(raw); }
; #pragma unroll
;             for (int m = 0; m < 4; ++m)
; #pragma unroll
;                 for (int n = 0; n < 2; ++n) { const size_t off = (size_t)(row0 + ai * 128 + m * 16) * 512 + cb + 4 * n;
;                     const f32x4 uv = ucv[m][n], sp = n ? sp1 : sp0, rb = n ? rb1 : rb0, ib = n ? ib1 : ib0; u32x4 pk;
; #pragma unroll
;                     for (int j = 0; j < 4; ++j) { const float r = sigmoidf_(acc[ai][0][m][n][j] + rb[j]), ig = sigmoidf_(acc[ai][1][m][n][j] + ib[j]);
;                         const float la = sp[j] * r; const float ae = __expf(la); const float om = 1.f - ae; pk[j] = cvt_pk_bf16(om, sqrtf(om * (1.f + ae)) * ig * uv[j]); }
;                     *(u32x4*)(AX + off) = pk; }
	v_sqrt_f32_e32 v231, v231
	v_pk_mul_f32 v[224:225], v[224:225], v[144:145]
	v_pk_mul_f32 v[226:227], v[226:227], v[146:147]
	v_pk_mul_f32 v[228:229], v[228:229], v[136:137]
	v_pk_mul_f32 v[230:231], v[230:231], v[138:139]
	v_cvt_pk_bf16_f32 v144, v148, v224
	v_cvt_pk_bf16_f32 v145, v149, v225
	v_cvt_pk_bf16_f32 v146, v150, v226
	v_cvt_pk_bf16_f32 v147, v151, v227
	v_cvt_pk_bf16_f32 v136, v140, v228
	v_cvt_pk_bf16_f32 v137, v141, v229
	v_cvt_pk_bf16_f32 v138, v142, v230
	v_cvt_pk_bf16_f32 v139, v143, v231
	s_add_u32 s98, s98, 0x4000
	s_addc_u32 s99, s99, 0
	global_load_dwordx4 v[244:247], v240, s[98:99]
	v_pk_fma_f32 v[132:133], v[132:133], v[222:223], v[204:205] op_sel_hi:[1,0,1]
	v_pk_fma_f32 v[134:135], v[134:135], v[222:223], v[206:207] op_sel_hi:[1,0,1]
	v_pk_fma_f32 v[124:125], v[124:125], v[222:223], v[208:209] op_sel_hi:[1,0,1]
	v_pk_fma_f32 v[126:127], v[126:127], v[222:223], v[210:211] op_sel_hi:[1,0,1]
	v_pk_fma_f32 v[128:129], v[128:129], v[222:223], v[212:213] op_sel_hi:[1,0,1]
	v_pk_fma_f32 v[130:131], v[130:131], v[222:223], v[214:215] op_sel_hi:[1,0,1]
	v_pk_fma_f32 v[120:121], v[120:121], v[222:223], v[216:217] op_sel_hi:[1,0,1]
	v_pk_fma_f32 v[122:123], v[122:123], v[222:223], v[218:219] op_sel_hi:[1,0,1]
	v_exp_f32_e32 v132, v132
	v_exp_f32_e32 v133, v133
	v_exp_f32_e32 v134, v134
	v_exp_f32_e32 v135, v135
	v_exp_f32_e32 v124, v124
	v_exp_f32_e32 v125, v125
	v_exp_f32_e32 v126, v126
	v_exp_f32_e32 v127, v127
	v_exp_f32_e32 v128, v128
	v_exp_f32_e32 v129, v129
	v_exp_f32_e32 v130, v130
	v_exp_f32_e32 v131, v131
	v_exp_f32_e32 v120, v120
	v_exp_f32_e32 v121, v121
	v_exp_f32_e32 v122, v122
	v_exp_f32_e32 v123, v123
	v_pk_add_f32 v[132:133], v[132:133], v[194:195] op_sel_hi:[1,0]
	v_pk_add_f32 v[134:135], v[134:135], v[194:195] op_sel_hi:[1,0]
	v_pk_add_f32 v[124:125], v[124:125], v[194:195] op_sel_hi:[1,0]
	v_pk_add_f32 v[126:127], v[126:127], v[194:195] op_sel_hi:[1,0]
	v_pk_add_f32 v[128:129], v[128:129], v[194:195] op_sel_hi:[1,0]
	v_pk_add_f32 v[130:131], v[130:131], v[194:195] op_sel_hi:[1,0]
	v_pk_add_f32 v[120:121], v[120:121], v[194:195] op_sel_hi:[1,0]
	v_pk_add_f32 v[122:123], v[122:123], v[194:195] op_sel_hi:[1,0]
	v_rcp_f32_e32 v132, v132
	v_rcp_f32_e32 v133, v133
	v_rcp_f32_e32 v134, v134
	v_rcp_f32_e32 v135, v135
	v_rcp_f32_e32 v124, v124
	v_rcp_f32_e32 v125, v125
	v_rcp_f32_e32 v126, v126
	v_rcp_f32_e32 v127, v127
	v_rcp_f32_e32 v128, v128
	v_rcp_f32_e32 v129, v129
	v_rcp_f32_e32 v130, v130
	v_rcp_f32_e32 v131, v131
	v_rcp_f32_e32 v120, v120
	v_rcp_f32_e32 v121, v121
	v_rcp_f32_e32 v122, v122
	v_rcp_f32_e32 v123, v123
	v_pk_mul_f32 v[132:133], v[132:133], v[196:197]
	v_pk_mul_f32 v[134:135], v[134:135], v[198:199]
	v_pk_mul_f32 v[124:125], v[124:125], v[200:201]
	v_pk_mul_f32 v[126:127], v[126:127], v[202:203]
	v_exp_f32_e32 v132, v132
	v_exp_f32_e32 v133, v133
	v_exp_f32_e32 v134, v134
	v_exp_f32_e32 v135, v135
	v_exp_f32_e32 v124, v124
	v_exp_f32_e32 v125, v125
	v_exp_f32_e32 v126, v126
	v_exp_f32_e32 v127, v127
	s_waitcnt vmcnt(1)
	v_lshlrev_b32_e32 v232, 16, v248
	v_and_b32_e32 v233, 0xffff0000, v248
	v_lshlrev_b32_e32 v234, 16, v249
	v_and_b32_e32 v235, 0xffff0000, v249
	v_lshlrev_b32_e32 v236, 16, v250
	v_and_b32_e32 v237, 0xffff0000, v250
	v_lshlrev_b32_e32 v238, 16, v251
	v_and_b32_e32 v239, 0xffff0000, v251
	v_pk_fma_f32 v[224:225], v[132:133], v[132:133], v[194:195] op_sel_hi:[1,1,0] neg_lo:[1,0,0] neg_hi:[1,0,0]
	v_pk_fma_f32 v[226:227], v[134:135], v[134:135], v[194:195] op_sel_hi:[1,1,0] neg_lo:[1,0,0] neg_hi:[1,0,0]
	v_pk_fma_f32 v[228:229], v[124:125], v[124:125], v[194:195] op_sel_hi:[1,1,0] neg_lo:[1,0,0] neg_hi:[1,0,0]
	v_pk_fma_f32 v[230:231], v[126:127], v[126:127], v[194:195] op_sel_hi:[1,1,0] neg_lo:[1,0,0] neg_hi:[1,0,0]
	v_pk_add_f32 v[132:133], v[194:195], v[132:133] op_sel_hi:[0,1] neg_lo:[0,1] neg_hi:[0,1]
	v_pk_add_f32 v[134:135], v[194:195], v[134:135] op_sel_hi:[0,1] neg_lo:[0,1] neg_hi:[0,1]
	v_pk_add_f32 v[124:125], v[194:195], v[124:125] op_sel_hi:[0,1] neg_lo:[0,1] neg_hi:[0,1]
	v_pk_add_f32 v[126:127], v[194:195], v[126:127] op_sel_hi:[0,1] neg_lo:[0,1] neg_hi:[0,1]
	v_pk_mul_f32 v[128:129], v[128:129], v[232:233]
	v_pk_mul_f32 v[130:131], v[130:131], v[234:235]
	v_pk_mul_f32 v[120:121], v[120:121], v[236:237]
	v_pk_mul_f32 v[122:123], v[122:123], v[238:239]
	v_sqrt_f32_e32 v224, v224
	v_sqrt_f32_e32 v225, v225
	v_sqrt_f32_e32 v226, v226
	v_sqrt_f32_e32 v227, v227
	v_sqrt_f32_e32 v228, v228
	v_sqrt_f32_e32 v229, v229
	v_sqrt_f32_e32 v230, v230
	v_sqrt_f32_e32 v231, v231
	v_pk_mul_f32 v[224:225], v[224:225], v[128:129]
	v_pk_mul_f32 v[226:227], v[226:227], v[130:131]
	v_pk_mul_f32 v[228:229], v[228:229], v[120:121]
	v_pk_mul_f32 v[230:231], v[230:231], v[122:123]
	v_cvt_pk_bf16_f32 v128, v132, v224
	v_cvt_pk_bf16_f32 v129, v133, v225
	v_cvt_pk_bf16_f32 v130, v134, v226
	v_cvt_pk_bf16_f32 v131, v135, v227
	v_cvt_pk_bf16_f32 v120, v124, v228
	v_cvt_pk_bf16_f32 v121, v125, v229
	v_cvt_pk_bf16_f32 v122, v126, v230
	v_cvt_pk_bf16_f32 v123, v127, v231
	s_add_u32 s98, s98, 0x4000
	s_addc_u32 s99, s99, 0
	global_load_dwordx4 v[248:251], v240, s[98:99]
	v_pk_fma_f32 v[116:117], v[116:117], v[222:223], v[204:205] op_sel_hi:[1,0,1]
	v_pk_fma_f32 v[118:119], v[118:119], v[222:223], v[206:207] op_sel_hi:[1,0,1]
	v_pk_fma_f32 v[108:109], v[108:109], v[222:223], v[208:209] op_sel_hi:[1,0,1]
	v_pk_fma_f32 v[110:111], v[110:111], v[222:223], v[210:211] op_sel_hi:[1,0,1]
	v_pk_fma_f32 v[112:113], v[112:113], v[222:223], v[212:213] op_sel_hi:[1,0,1]
	v_pk_fma_f32 v[114:115], v[114:115], v[222:223], v[214:215] op_sel_hi:[1,0,1]
	v_pk_fma_f32 v[104:105], v[104:105], v[222:223], v[216:217] op_sel_hi:[1,0,1]
; __device__ __forceinline__ unsigned cvt_pk_bf16(float lo, float hi) { unsigned r; asm volatile("v_cvt_pk_bf16_f32 %0, %1, %2" : "=v"(r) : "v"(lo), "v"(hi)); return r; }
; __device__ __forceinline__ float sigmoidf_(float x) { return 1.f / (1.f + __expf(-x)); }
; __device__ __forceinline__ f32x4 bf4lo(u32x4 r) { return (f32x4){__uint_as_float(r.x << 16), __uint_as_float(r.x & 0xffff0000u), __uint_as_float(r.y << 16), __uint_as_float(r.y & 0xffff0000u)}; }
; __device__ __forceinline__ f32x4 bf4hi(u32x4 r) { return (f32x4){__uint_as_float(r.z << 16), __uint_as_float(r.z & 0xffff0000u), __uint_as_float(r.w << 16), __uint_as_float(r.w & 0xffff0000u)}; }
;     __device__ __forceinline__ void operator()(const f32x4 (&acc)[2][2][4][2], const Unit& u, int wr, int wc, int fr, int fq) const {
;     ...
;             for (int m = 0; m < 4; ++m) { const u32x4 raw = *(const u32x4*)(UCBp + (size_t)(row0 + ai * 128 + m * 16) * 512 + cb); ucv[m][0] = bf4lo(raw); ucv[m][1] = bf4hi(raw); }
; #pragma unroll
;             for (int m = 0; m < 4; ++m)
; #pragma unroll
;                 for (int n = 0; n < 2; ++n) { const size_t off = (size_t)(row0 + ai * 128 + m * 16) * 512 + cb + 4 * n;
;                     const f32x4 uv = ucv[m][n], sp = n ? sp1 : sp0, rb = n ? rb1 : rb0, ib = n ? ib1 : ib0; u32x4 pk;
; #pragma unroll
;                     for (int j = 0; j < 4; ++j) { const float r = sigmoidf_(acc[ai][0][m][n][j] + rb[j]), ig = sigmoidf_(acc[ai][1][m][n][j] + ib[j]);
;                         const float la = sp[j] * r; const float ae = __expf(la); const float om = 1.f - ae; pk[j] = cvt_pk_bf16(om, sqrtf(om * (1.f + ae)) * ig * uv[j]); }
;                     *(u32x4*)(AX + off) = pk; }
	v_pk_fma_f32 v[106:107], v[106:107], v[222:223], v[218:219] op_sel_hi:[1,0,1]
	v_exp_f32_e32 v116, v116
	v_exp_f32_e32 v117, v117
	v_exp_f32_e32 v118, v118
	v_exp_f32_e32 v119, v119
	v_exp_f32_e32 v108, v108
	v_exp_f32_e32 v109, v109
	v_exp_f32_e32 v110, v110
	v_exp_f32_e32 v111, v111
	v_exp_f32_e32 v112, v112
	v_exp_f32_e32 v113, v113
	v_exp_f32_e32 v114, v114
	v_exp_f32_e32 v115, v115
	v_exp_f32_e32 v104, v104
	v_exp_f32_e32 v105, v105
	v_exp_f32_e32 v106, v106
	v_exp_f32_e32 v107, v107
	v_pk_add_f32 v[116:117], v[116:117], v[194:195] op_sel_hi:[1,0]
	v_pk_add_f32 v[118:119], v[118:119], v[194:195] op_sel_hi:[1,0]
	v_pk_add_f32 v[108:109], v[108:109], v[194:195] op_sel_hi:[1,0]
	v_pk_add_f32 v[110:111], v[110:111], v[194:195] op_sel_hi:[1,0]
	v_pk_add_f32 v[112:113], v[112:113], v[194:195] op_sel_hi:[1,0]
	v_pk_add_f32 v[114:115], v[114:115], v[194:195] op_sel_hi:[1,0]
	v_pk_add_f32 v[104:105], v[104:105], v[194:195] op_sel_hi:[1,0]
	v_pk_add_f32 v[106:107], v[106:107], v[194:195] op_sel_hi:[1,0]
	v_rcp_f32_e32 v116, v116
	v_rcp_f32_e32 v117, v117
	v_rcp_f32_e32 v118, v118
	v_rcp_f32_e32 v119, v119
	v_rcp_f32_e32 v108, v108
	v_rcp_f32_e32 v109, v109
	v_rcp_f32_e32 v110, v110
	v_rcp_f32_e32 v111, v111
	v_rcp_f32_e32 v112, v112
	v_rcp_f32_e32 v113, v113
	v_rcp_f32_e32 v114, v114
	v_rcp_f32_e32 v115, v115
	v_rcp_f32_e32 v104, v104
	v_rcp_f32_e32 v105, v105
	v_rcp_f32_e32 v106, v106
	v_rcp_f32_e32 v107, v107
	v_pk_mul_f32 v[116:117], v[116:117], v[196:197]
	v_pk_mul_f32 v[118:119], v[118:119], v[198:199]
	v_pk_mul_f32 v[108:109], v[108:109], v[200:201]
	v_pk_mul_f32 v[110:111], v[110:111], v[202:203]
	v_exp_f32_e32 v116, v116
	v_exp_f32_e32 v117, v117
	v_exp_f32_e32 v118, v118
	v_exp_f32_e32 v119, v119
	v_exp_f32_e32 v108, v108
	v_exp_f32_e32 v109, v109
	v_exp_f32_e32 v110, v110
	v_exp_f32_e32 v111, v111
	s_waitcnt vmcnt(1)
	v_lshlrev_b32_e32 v232, 16, v244
	v_and_b32_e32 v233, 0xffff0000, v244
	v_lshlrev_b32_e32 v234, 16, v245
	v_and_b32_e32 v235, 0xffff0000, v245
	v_lshlrev_b32_e32 v236, 16, v246
	v_and_b32_e32 v237, 0xffff0000, v246
	v_lshlrev_b32_e32 v238, 16, v247
	v_and_b32_e32 v239, 0xffff0000, v247
	v_pk_fma_f32 v[224:225], v[116:117], v[116:117], v[194:195] op_sel_hi:[1,1,0] neg_lo:[1,0,0] neg_hi:[1,0,0]
	v_pk_fma_f32 v[226:227], v[118:119], v[118:119], v[194:195] op_sel_hi:[1,1,0] neg_lo:[1,0,0] neg_hi:[1,0,0]
	v_pk_fma_f32 v[228:229], v[108:109], v[108:109], v[194:195] op_sel_hi:[1,1,0] neg_lo:[1,0,0] neg_hi:[1,0,0]
	v_pk_fma_f32 v[230:231], v[110:111], v[110:111], v[194:195] op_sel_hi:[1,1,0] neg_lo:[1,0,0] neg_hi:[1,0,0]
	v_pk_add_f32 v[116:117], v[194:195], v[116:117] op_sel_hi:[0,1] neg_lo:[0,1] neg_hi:[0,1]
	v_pk_add_f32 v[118:119], v[194:195], v[118:119] op_sel_hi:[0,1] neg_lo:[0,1] neg_hi:[0,1]
	v_pk_add_f32 v[108:109], v[194:195], v[108:109] op_sel_hi:[0,1] neg_lo:[0,1] neg_hi:[0,1]
	v_pk_add_f32 v[110:111], v[194:195], v[110:111] op_sel_hi:[0,1] neg_lo:[0,1] neg_hi:[0,1]
	v_pk_mul_f32 v[112:113], v[112:113], v[232:233]
	v_pk_mul_f32 v[114:115], v[114:115], v[234:235]
	v_pk_mul_f32 v[104:105], v[104:105], v[236:237]
	v_pk_mul_f32 v[106:107], v[106:107], v[238:239]
	v_sqrt_f32_e32 v224, v224
	v_sqrt_f32_e32 v225, v225
	v_sqrt_f32_e32 v226, v226
	v_sqrt_f32_e32 v227, v227
	v_sqrt_f32_e32 v228, v228
	v_sqrt_f32_e32 v229, v229
	v_sqrt_f32_e32 v230, v230
	v_sqrt_f32_e32 v231, v231
	v_pk_mul_f32 v[224:225], v[224:225], v[112:113]
	v_pk_mul_f32 v[226:227], v[226:227], v[114:115]
	v_pk_mul_f32 v[228:229], v[228:229], v[104:105]
	v_pk_mul_f32 v[230:231], v[230:231], v[106:107]
	v_cvt_pk_bf16_f32 v112, v116, v224
	v_cvt_pk_bf16_f32 v113, v117, v225
	v_cvt_pk_bf16_f32 v114, v118, v226
	v_cvt_pk_bf16_f32 v115, v119, v227
	v_cvt_pk_bf16_f32 v104, v108, v228
	v_cvt_pk_bf16_f32 v105, v109, v229
	v_cvt_pk_bf16_f32 v106, v110, v230
	v_cvt_pk_bf16_f32 v107, v111, v231
	s_add_u32 s98, s98, 0x14000
	s_addc_u32 s99, s99, 0
	global_load_dwordx4 v[244:247], v240, s[98:99]
	v_pk_fma_f32 v[100:101], v[100:101], v[222:223], v[204:205] op_sel_hi:[1,0,1]
	v_pk_fma_f32 v[102:103], v[102:103], v[222:223], v[206:207] op_sel_hi:[1,0,1]
	v_pk_fma_f32 v[92:93], v[92:93], v[222:223], v[208:209] op_sel_hi:[1,0,1]
	v_pk_fma_f32 v[94:95], v[94:95], v[222:223], v[210:211] op_sel_hi:[1,0,1]
	v_pk_fma_f32 v[96:97], v[96:97], v[222:223], v[212:213] op_sel_hi:[1,0,1]
	v_pk_fma_f32 v[98:99], v[98:99], v[222:223], v[214:215] op_sel_hi:[1,0,1]
	v_pk_fma_f32 v[88:89], v[88:89], v[222:223], v[216:217] op_sel_hi:[1,0,1]
	v_pk_fma_f32 v[90:91], v[90:91], v[222:223], v[218:219] op_sel_hi:[1,0,1]
	v_exp_f32_e32 v100, v100
	v_exp_f32_e32 v101, v101
	v_exp_f32_e32 v102, v102
	v_exp_f32_e32 v103, v103
	v_exp_f32_e32 v92, v92
	v_exp_f32_e32 v93, v93
	v_exp_f32_e32 v94, v94
	v_exp_f32_e32 v95, v95
	v_exp_f32_e32 v96, v96
	v_exp_f32_e32 v97, v97
	v_exp_f32_e32 v98, v98
	v_exp_f32_e32 v99, v99
	v_exp_f32_e32 v88, v88
	v_exp_f32_e32 v89, v89
	v_exp_f32_e32 v90, v90
	v_exp_f32_e32 v91, v91
	v_pk_add_f32 v[100:101], v[100:101], v[194:195] op_sel_hi:[1,0]
	v_pk_add_f32 v[102:103], v[102:103], v[194:195] op_sel_hi:[1,0]
	v_pk_add_f32 v[92:93], v[92:93], v[194:195] op_sel_hi:[1,0]
	v_pk_add_f32 v[94:95], v[94:95], v[194:195] op_sel_hi:[1,0]
	v_pk_add_f32 v[96:97], v[96:97], v[194:195] op_sel_hi:[1,0]
	v_pk_add_f32 v[98:99], v[98:99], v[194:195] op_sel_hi:[1,0]
	v_pk_add_f32 v[88:89], v[88:89], v[194:195] op_sel_hi:[1,0]
	v_pk_add_f32 v[90:91], v[90:91], v[194:195] op_sel_hi:[1,0]
	v_rcp_f32_e32 v100, v100
	v_rcp_f32_e32 v101, v101
	v_rcp_f32_e32 v102, v102
	v_rcp_f32_e32 v103, v103
	v_rcp_f32_e32 v92, v92
	v_rcp_f32_e32 v93, v93
	v_rcp_f32_e32 v94, v94
	v_rcp_f32_e32 v95, v95
	v_rcp_f32_e32 v96, v96
	v_rcp_f32_e32 v97, v97
	v_rcp_f32_e32 v98, v98
	v_rcp_f32_e32 v99, v99
	v_rcp_f32_e32 v88, v88
	v_rcp_f32_e32 v89, v89
	v_rcp_f32_e32 v90, v90
	v_rcp_f32_e32 v91, v91
	v_pk_mul_f32 v[100:101], v[100:101], v[196:197]
	v_pk_mul_f32 v[102:103], v[102:103], v[198:199]
	v_pk_mul_f32 v[92:93], v[92:93], v[200:201]
	v_pk_mul_f32 v[94:95], v[94:95], v[202:203]
	v_exp_f32_e32 v100, v100
	v_exp_f32_e32 v101, v101
	v_exp_f32_e32 v102, v102
	v_exp_f32_e32 v103, v103
	v_exp_f32_e32 v92, v92
	v_exp_f32_e32 v93, v93
	v_exp_f32_e32 v94, v94
	v_exp_f32_e32 v95, v95
	s_waitcnt vmcnt(1)
; __device__ __forceinline__ unsigned cvt_pk_bf16(float lo, float hi) { unsigned r; asm volatile("v_cvt_pk_bf16_f32 %0, %1, %2" : "=v"(r) : "v"(lo), "v"(hi)); return r; }
; __device__ __forceinline__ float sigmoidf_(float x) { return 1.f / (1.f + __expf(-x)); }
; __device__ __forceinline__ f32x4 bf4lo(u32x4 r) { return (f32x4){__uint_as_float(r.x << 16), __uint_as_float(r.x & 0xffff0000u), __uint_as_float(r.y << 16), __uint_as_float(r.y & 0xffff0000u)}; }
; __device__ __forceinline__ f32x4 bf4hi(u32x4 r) { return (f32x4){__uint_as_float(r.z << 16), __uint_as_float(r.z & 0xffff0000u), __uint_as_float(r.w << 16), __uint_as_float(r.w & 0xffff0000u)}; }
;     __device__ __forceinline__ void operator()(const f32x4 (&acc)[2][2][4][2], const Unit& u, int wr, int wc, int fr, int fq) const {
;     ...
;             for (int m = 0; m < 4; ++m) { const u32x4 raw = *(const u32x4*)(UCBp + (size_t)(row0 + ai * 128 + m * 16) * 512 + cb); ucv[m][0] = bf4lo(raw); ucv[m][1] = bf4hi(raw); }
; #pragma unroll
;             for (int m = 0; m < 4; ++m)
; #pragma unroll
;                 for (int n = 0; n < 2; ++n) { const size_t off = (size_t)(row0 + ai * 128 + m * 16) * 512 + cb + 4 * n;
;                     const f32x4 uv = ucv[m][n], sp = n ? sp1 : sp0, rb = n ? rb1 : rb0, ib = n ? ib1 : ib0; u32x4 pk;
; #pragma unroll
;                     for (int j = 0; j < 4; ++j) { const float r = sigmoidf_(acc[ai][0][m][n][j] + rb[j]), ig = sigmoidf_(acc[ai][1][m][n][j] + ib[j]);
;                         const float la = sp[j] * r; const float ae = __expf(la); const float om = 1.f - ae; pk[j] = cvt_pk_bf16(om, sqrtf(om * (1.f + ae)) * ig * uv[j]); }
;                     *(u32x4*)(AX + off) = pk; }
	v_lshlrev_b32_e32 v232, 16, v248
	v_and_b32_e32 v233, 0xffff0000, v248
	v_lshlrev_b32_e32 v234, 16, v249
	v_and_b32_e32 v235, 0xffff0000, v249
	v_lshlrev_b32_e32 v236, 16, v250
	v_and_b32_e32 v237, 0xffff0000, v250
	v_lshlrev_b32_e32 v238, 16, v251
	v_and_b32_e32 v239, 0xffff0000, v251
	v_pk_fma_f32 v[224:225], v[100:101], v[100:101], v[194:195] op_sel_hi:[1,1,0] neg_lo:[1,0,0] neg_hi:[1,0,0]
	v_pk_fma_f32 v[226:227], v[102:103], v[102:103], v[194:195] op_sel_hi:[1,1,0] neg_lo:[1,0,0] neg_hi:[1,0,0]
	v_pk_fma_f32 v[228:229], v[92:93], v[92:93], v[194:195] op_sel_hi:[1,1,0] neg_lo:[1,0,0] neg_hi:[1,0,0]
	v_pk_fma_f32 v[230:231], v[94:95], v[94:95], v[194:195] op_sel_hi:[1,1,0] neg_lo:[1,0,0] neg_hi:[1,0,0]
	v_pk_add_f32 v[100:101], v[194:195], v[100:101] op_sel_hi:[0,1] neg_lo:[0,1] neg_hi:[0,1]
	v_pk_add_f32 v[102:103], v[194:195], v[102:103] op_sel_hi:[0,1] neg_lo:[0,1] neg_hi:[0,1]
	v_pk_add_f32 v[92:93], v[194:195], v[92:93] op_sel_hi:[0,1] neg_lo:[0,1] neg_hi:[0,1]
	v_pk_add_f32 v[94:95], v[194:195], v[94:95] op_sel_hi:[0,1] neg_lo:[0,1] neg_hi:[0,1]
	v_pk_mul_f32 v[96:97], v[96:97], v[232:233]
	v_pk_mul_f32 v[98:99], v[98:99], v[234:235]
	v_pk_mul_f32 v[88:89], v[88:89], v[236:237]
	v_pk_mul_f32 v[90:91], v[90:91], v[238:239]
	v_sqrt_f32_e32 v224, v224
	v_sqrt_f32_e32 v225, v225
	v_sqrt_f32_e32 v226, v226
	v_sqrt_f32_e32 v227, v227
	v_sqrt_f32_e32 v228, v228
	v_sqrt_f32_e32 v229, v229
	v_sqrt_f32_e32 v230, v230
	v_sqrt_f32_e32 v231, v231
	v_pk_mul_f32 v[224:225], v[224:225], v[96:97]
	v_pk_mul_f32 v[226:227], v[226:227], v[98:99]
	v_pk_mul_f32 v[228:229], v[228:229], v[88:89]
	v_pk_mul_f32 v[230:231], v[230:231], v[90:91]
	v_cvt_pk_bf16_f32 v96, v100, v224
	v_cvt_pk_bf16_f32 v97, v101, v225
	v_cvt_pk_bf16_f32 v98, v102, v226
	v_cvt_pk_bf16_f32 v99, v103, v227
	v_cvt_pk_bf16_f32 v88, v92, v228
	v_cvt_pk_bf16_f32 v89, v93, v229
	v_cvt_pk_bf16_f32 v90, v94, v230
	v_cvt_pk_bf16_f32 v91, v95, v231
	s_add_u32 s98, s98, 0x4000
	s_addc_u32 s99, s99, 0
	global_load_dwordx4 v[248:251], v240, s[98:99]
	v_pk_fma_f32 v[84:85], v[84:85], v[222:223], v[204:205] op_sel_hi:[1,0,1]
	v_pk_fma_f32 v[86:87], v[86:87], v[222:223], v[206:207] op_sel_hi:[1,0,1]
	v_pk_fma_f32 v[76:77], v[76:77], v[222:223], v[208:209] op_sel_hi:[1,0,1]
	v_pk_fma_f32 v[78:79], v[78:79], v[222:223], v[210:211] op_sel_hi:[1,0,1]
	v_pk_fma_f32 v[80:81], v[80:81], v[222:223], v[212:213] op_sel_hi:[1,0,1]
	v_pk_fma_f32 v[82:83], v[82:83], v[222:223], v[214:215] op_sel_hi:[1,0,1]
	v_pk_fma_f32 v[72:73], v[72:73], v[222:223], v[216:217] op_sel_hi:[1,0,1]
	v_pk_fma_f32 v[74:75], v[74:75], v[222:223], v[218:219] op_sel_hi:[1,0,1]
	v_exp_f32_e32 v84, v84
	v_exp_f32_e32 v85, v85
	v_exp_f32_e32 v86, v86
	v_exp_f32_e32 v87, v87
	v_exp_f32_e32 v76, v76
	v_exp_f32_e32 v77, v77
	v_exp_f32_e32 v78, v78
	v_exp_f32_e32 v79, v79
	v_exp_f32_e32 v80, v80
	v_exp_f32_e32 v81, v81
	v_exp_f32_e32 v82, v82
	v_exp_f32_e32 v83, v83
	v_exp_f32_e32 v72, v72
	v_exp_f32_e32 v73, v73
	v_exp_f32_e32 v74, v74
	v_exp_f32_e32 v75, v75
	v_pk_add_f32 v[84:85], v[84:85], v[194:195] op_sel_hi:[1,0]
	v_pk_add_f32 v[86:87], v[86:87], v[194:195] op_sel_hi:[1,0]
	v_pk_add_f32 v[76:77], v[76:77], v[194:195] op_sel_hi:[1,0]
	v_pk_add_f32 v[78:79], v[78:79], v[194:195] op_sel_hi:[1,0]
	v_pk_add_f32 v[80:81], v[80:81], v[194:195] op_sel_hi:[1,0]
	v_pk_add_f32 v[82:83], v[82:83], v[194:195] op_sel_hi:[1,0]
	v_pk_add_f32 v[72:73], v[72:73], v[194:195] op_sel_hi:[1,0]
	v_pk_add_f32 v[74:75], v[74:75], v[194:195] op_sel_hi:[1,0]
	v_rcp_f32_e32 v84, v84
	v_rcp_f32_e32 v85, v85
	v_rcp_f32_e32 v86, v86
	v_rcp_f32_e32 v87, v87
	v_rcp_f32_e32 v76, v76
	v_rcp_f32_e32 v77, v77
	v_rcp_f32_e32 v78, v78
	v_rcp_f32_e32 v79, v79
	v_rcp_f32_e32 v80, v80
	v_rcp_f32_e32 v81, v81
	v_rcp_f32_e32 v82, v82
	v_rcp_f32_e32 v83, v83
	v_rcp_f32_e32 v72, v72
	v_rcp_f32_e32 v73, v73
	v_rcp_f32_e32 v74, v74
	v_rcp_f32_e32 v75, v75
	v_pk_mul_f32 v[84:85], v[84:85], v[196:197]
	v_pk_mul_f32 v[86:87], v[86:87], v[198:199]
	v_pk_mul_f32 v[76:77], v[76:77], v[200:201]
	v_pk_mul_f32 v[78:79], v[78:79], v[202:203]
	v_exp_f32_e32 v84, v84
	v_exp_f32_e32 v85, v85
	v_exp_f32_e32 v86, v86
	v_exp_f32_e32 v87, v87
	v_exp_f32_e32 v76, v76
	v_exp_f32_e32 v77, v77
	v_exp_f32_e32 v78, v78
	v_exp_f32_e32 v79, v79
	s_waitcnt vmcnt(1)
; __device__ __forceinline__ unsigned cvt_pk_bf16(float lo, float hi) { unsigned r; asm volatile("v_cvt_pk_bf16_f32 %0, %1, %2" : "=v"(r) : "v"(lo), "v"(hi)); return r; }
; __device__ __forceinline__ float sigmoidf_(float x) { return 1.f / (1.f + __expf(-x)); }
; __device__ __forceinline__ f32x4 bf4lo(u32x4 r) { return (f32x4){__uint_as_float(r.x << 16), __uint_as_float(r.x & 0xffff0000u), __uint_as_float(r.y << 16), __uint_as_float(r.y & 0xffff0000u)}; }
; __device__ __forceinline__ f32x4 bf4hi(u32x4 r) { return (f32x4){__uint_as_float(r.z << 16), __uint_as_float(r.z & 0xffff0000u), __uint_as_float(r.w << 16), __uint_as_float(r.w & 0xffff0000u)}; }
;     __device__ __forceinline__ void operator()(const f32x4 (&acc)[2][2][4][2], const Unit& u, int wr, int wc, int fr, int fq) const {
;     ...
;             for (int m = 0; m < 4; ++m) { const u32x4 raw = *(const u32x4*)(UCBp + (size_t)(row0 + ai * 128 + m * 16) * 512 + cb); ucv[m][0] = bf4lo(raw); ucv[m][1] = bf4hi(raw); }
; #pragma unroll
;             for (int m = 0; m < 4; ++m)
; #pragma unroll
;                 for (int n = 0; n < 2; ++n) { const size_t off = (size_t)(row0 + ai * 128 + m * 16) * 512 + cb + 4 * n;
;                     const f32x4 uv = ucv[m][n], sp = n ? sp1 : sp0, rb = n ? rb1 : rb0, ib = n ? ib1 : ib0; u32x4 pk;
; #pragma unroll
;                     for (int j = 0; j < 4; ++j) { const float r = sigmoidf_(acc[ai][0][m][n][j] + rb[j]), ig = sigmoidf_(acc[ai][1][m][n][j] + ib[j]);
;                         const float la = sp[j] * r; const float ae = __expf(la); const float om = 1.f - ae; pk[j] = cvt_pk_bf16(om, sqrtf(om * (1.f + ae)) * ig * uv[j]); }
;                     *(u32x4*)(AX + off) = pk; }
	v_lshlrev_b32_e32 v232, 16, v244
	v_and_b32_e32 v233, 0xffff0000, v244
	v_lshlrev_b32_e32 v234, 16, v245
	v_and_b32_e32 v235, 0xffff0000, v245
	v_lshlrev_b32_e32 v236, 16, v246
	v_and_b32_e32 v237, 0xffff0000, v246
	v_lshlrev_b32_e32 v238, 16, v247
	v_and_b32_e32 v239, 0xffff0000, v247
	v_pk_fma_f32 v[224:225], v[84:85], v[84:85], v[194:195] op_sel_hi:[1,1,0] neg_lo:[1,0,0] neg_hi:[1,0,0]
	v_pk_fma_f32 v[226:227], v[86:87], v[86:87], v[194:195] op_sel_hi:[1,1,0] neg_lo:[1,0,0] neg_hi:[1,0,0]
	v_pk_fma_f32 v[228:229], v[76:77], v[76:77], v[194:195] op_sel_hi:[1,1,0] neg_lo:[1,0,0] neg_hi:[1,0,0]
	v_pk_fma_f32 v[230:231], v[78:79], v[78:79], v[194:195] op_sel_hi:[1,1,0] neg_lo:[1,0,0] neg_hi:[1,0,0]
	v_pk_add_f32 v[84:85], v[194:195], v[84:85] op_sel_hi:[0,1] neg_lo:[0,1] neg_hi:[0,1]
	v_pk_add_f32 v[86:87], v[194:195], v[86:87] op_sel_hi:[0,1] neg_lo:[0,1] neg_hi:[0,1]
	v_pk_add_f32 v[76:77], v[194:195], v[76:77] op_sel_hi:[0,1] neg_lo:[0,1] neg_hi:[0,1]
	v_pk_add_f32 v[78:79], v[194:195], v[78:79] op_sel_hi:[0,1] neg_lo:[0,1] neg_hi:[0,1]
	v_pk_mul_f32 v[80:81], v[80:81], v[232:233]
	v_pk_mul_f32 v[82:83], v[82:83], v[234:235]
	v_pk_mul_f32 v[72:73], v[72:73], v[236:237]
	v_pk_mul_f32 v[74:75], v[74:75], v[238:239]
	v_sqrt_f32_e32 v224, v224
	v_sqrt_f32_e32 v225, v225
	v_sqrt_f32_e32 v226, v226
	v_sqrt_f32_e32 v227, v227
	v_sqrt_f32_e32 v228, v228
	v_sqrt_f32_e32 v229, v229
	v_sqrt_f32_e32 v230, v230
	v_sqrt_f32_e32 v231, v231
	v_pk_mul_f32 v[224:225], v[224:225], v[80:81]
	v_pk_mul_f32 v[226:227], v[226:227], v[82:83]
	v_pk_mul_f32 v[228:229], v[228:229], v[72:73]
	v_pk_mul_f32 v[230:231], v[230:231], v[74:75]
	v_cvt_pk_bf16_f32 v80, v84, v224
	v_cvt_pk_bf16_f32 v81, v85, v225
	v_cvt_pk_bf16_f32 v82, v86, v226
	v_cvt_pk_bf16_f32 v83, v87, v227
	v_cvt_pk_bf16_f32 v72, v76, v228
	v_cvt_pk_bf16_f32 v73, v77, v229
	v_cvt_pk_bf16_f32 v74, v78, v230
	v_cvt_pk_bf16_f32 v75, v79, v231
	s_add_u32 s98, s98, 0x4000
	s_addc_u32 s99, s99, 0
	global_load_dwordx4 v[244:247], v240, s[98:99]
	v_pk_fma_f32 v[68:69], v[68:69], v[222:223], v[204:205] op_sel_hi:[1,0,1]
	v_pk_fma_f32 v[70:71], v[70:71], v[222:223], v[206:207] op_sel_hi:[1,0,1]
	v_pk_fma_f32 v[60:61], v[60:61], v[222:223], v[208:209] op_sel_hi:[1,0,1]
	v_pk_fma_f32 v[62:63], v[62:63], v[222:223], v[210:211] op_sel_hi:[1,0,1]
	v_pk_fma_f32 v[64:65], v[64:65], v[222:223], v[212:213] op_sel_hi:[1,0,1]
	v_pk_fma_f32 v[66:67], v[66:67], v[222:223], v[214:215] op_sel_hi:[1,0,1]
	v_pk_fma_f32 v[56:57], v[56:57], v[222:223], v[216:217] op_sel_hi:[1,0,1]
	v_pk_fma_f32 v[58:59], v[58:59], v[222:223], v[218:219] op_sel_hi:[1,0,1]
	v_exp_f32_e32 v68, v68
	v_exp_f32_e32 v69, v69
	v_exp_f32_e32 v70, v70
	v_exp_f32_e32 v71, v71
	v_exp_f32_e32 v60, v60
	v_exp_f32_e32 v61, v61
	v_exp_f32_e32 v62, v62
	v_exp_f32_e32 v63, v63
	v_exp_f32_e32 v64, v64
	v_exp_f32_e32 v65, v65
	v_exp_f32_e32 v66, v66
	v_exp_f32_e32 v67, v67
	v_exp_f32_e32 v56, v56
	v_exp_f32_e32 v57, v57
	v_exp_f32_e32 v58, v58
	v_exp_f32_e32 v59, v59
	v_pk_add_f32 v[68:69], v[68:69], v[194:195] op_sel_hi:[1,0]
	v_pk_add_f32 v[70:71], v[70:71], v[194:195] op_sel_hi:[1,0]
	v_pk_add_f32 v[60:61], v[60:61], v[194:195] op_sel_hi:[1,0]
	v_pk_add_f32 v[62:63], v[62:63], v[194:195] op_sel_hi:[1,0]
	v_pk_add_f32 v[64:65], v[64:65], v[194:195] op_sel_hi:[1,0]
	v_pk_add_f32 v[66:67], v[66:67], v[194:195] op_sel_hi:[1,0]
	v_pk_add_f32 v[56:57], v[56:57], v[194:195] op_sel_hi:[1,0]
	v_pk_add_f32 v[58:59], v[58:59], v[194:195] op_sel_hi:[1,0]
	v_rcp_f32_e32 v68, v68
	v_rcp_f32_e32 v69, v69
	v_rcp_f32_e32 v70, v70
	v_rcp_f32_e32 v71, v71
	v_rcp_f32_e32 v60, v60
	v_rcp_f32_e32 v61, v61
	v_rcp_f32_e32 v62, v62
	v_rcp_f32_e32 v63, v63
	v_rcp_f32_e32 v64, v64
	v_rcp_f32_e32 v65, v65
	v_rcp_f32_e32 v66, v66
	v_rcp_f32_e32 v67, v67
	v_rcp_f32_e32 v56, v56
	v_rcp_f32_e32 v57, v57
	v_rcp_f32_e32 v58, v58
	v_rcp_f32_e32 v59, v59
	v_pk_mul_f32 v[68:69], v[68:69], v[196:197]
	v_pk_mul_f32 v[70:71], v[70:71], v[198:199]
	v_pk_mul_f32 v[60:61], v[60:61], v[200:201]
	v_pk_mul_f32 v[62:63], v[62:63], v[202:203]
	v_exp_f32_e32 v68, v68
	v_exp_f32_e32 v69, v69
	v_exp_f32_e32 v70, v70
	v_exp_f32_e32 v71, v71
	v_exp_f32_e32 v60, v60
	v_exp_f32_e32 v61, v61
	v_exp_f32_e32 v62, v62
	v_exp_f32_e32 v63, v63
	s_waitcnt vmcnt(1)
; __device__ __forceinline__ unsigned cvt_pk_bf16(float lo, float hi) { unsigned r; asm volatile("v_cvt_pk_bf16_f32 %0, %1, %2" : "=v"(r) : "v"(lo), "v"(hi)); return r; }
; __device__ __forceinline__ float sigmoidf_(float x) { return 1.f / (1.f + __expf(-x)); }
; __device__ __forceinline__ f32x4 bf4lo(u32x4 r) { return (f32x4){__uint_as_float(r.x << 16), __uint_as_float(r.x & 0xffff0000u), __uint_as_float(r.y << 16), __uint_as_float(r.y & 0xffff0000u)}; }
; __device__ __forceinline__ f32x4 bf4hi(u32x4 r) { return (f32x4){__uint_as_float(r.z << 16), __uint_as_float(r.z & 0xffff0000u), __uint_as_float(r.w << 16), __uint_as_float(r.w & 0xffff0000u)}; }
;     __device__ __forceinline__ void operator()(const f32x4 (&acc)[2][2][4][2], const Unit& u, int wr, int wc, int fr, int fq) const {
;     ...
;             for (int m = 0; m < 4; ++m) { const u32x4 raw = *(const u32x4*)(UCBp + (size_t)(row0 + ai * 128 + m * 16) * 512 + cb); ucv[m][0] = bf4lo(raw); ucv[m][1] = bf4hi(raw); }
; #pragma unroll
;             for (int m = 0; m < 4; ++m)
; #pragma unroll
;                 for (int n = 0; n < 2; ++n) { const size_t off = (size_t)(row0 + ai * 128 + m * 16) * 512 + cb + 4 * n;
;                     const f32x4 uv = ucv[m][n], sp = n ? sp1 : sp0, rb = n ? rb1 : rb0, ib = n ? ib1 : ib0; u32x4 pk;
; #pragma unroll
;                     for (int j = 0; j < 4; ++j) { const float r = sigmoidf_(acc[ai][0][m][n][j] + rb[j]), ig = sigmoidf_(acc[ai][1][m][n][j] + ib[j]);
;                         const float la = sp[j] * r; const float ae = __expf(la); const float om = 1.f - ae; pk[j] = cvt_pk_bf16(om, sqrtf(om * (1.f + ae)) * ig * uv[j]); }
;                     *(u32x4*)(AX + off) = pk; }
	v_lshlrev_b32_e32 v232, 16, v248
	v_and_b32_e32 v233, 0xffff0000, v248
	v_lshlrev_b32_e32 v234, 16, v249
	v_and_b32_e32 v235, 0xffff0000, v249
	v_lshlrev_b32_e32 v236, 16, v250
	v_and_b32_e32 v237, 0xffff0000, v250
	v_lshlrev_b32_e32 v238, 16, v251
	v_and_b32_e32 v239, 0xffff0000, v251
	v_pk_fma_f32 v[224:225], v[68:69], v[68:69], v[194:195] op_sel_hi:[1,1,0] neg_lo:[1,0,0] neg_hi:[1,0,0]
	v_pk_fma_f32 v[226:227], v[70:71], v[70:71], v[194:195] op_sel_hi:[1,1,0] neg_lo:[1,0,0] neg_hi:[1,0,0]
	v_pk_fma_f32 v[228:229], v[60:61], v[60:61], v[194:195] op_sel_hi:[1,1,0] neg_lo:[1,0,0] neg_hi:[1,0,0]
	v_pk_fma_f32 v[230:231], v[62:63], v[62:63], v[194:195] op_sel_hi:[1,1,0] neg_lo:[1,0,0] neg_hi:[1,0,0]
	v_pk_add_f32 v[68:69], v[194:195], v[68:69] op_sel_hi:[0,1] neg_lo:[0,1] neg_hi:[0,1]
	v_pk_add_f32 v[70:71], v[194:195], v[70:71] op_sel_hi:[0,1] neg_lo:[0,1] neg_hi:[0,1]
	v_pk_add_f32 v[60:61], v[194:195], v[60:61] op_sel_hi:[0,1] neg_lo:[0,1] neg_hi:[0,1]
	v_pk_add_f32 v[62:63], v[194:195], v[62:63] op_sel_hi:[0,1] neg_lo:[0,1] neg_hi:[0,1]
	v_pk_mul_f32 v[64:65], v[64:65], v[232:233]
	v_pk_mul_f32 v[66:67], v[66:67], v[234:235]
	v_pk_mul_f32 v[56:57], v[56:57], v[236:237]
	v_pk_mul_f32 v[58:59], v[58:59], v[238:239]
	v_sqrt_f32_e32 v224, v224
	v_sqrt_f32_e32 v225, v225
	v_sqrt_f32_e32 v226, v226
	v_sqrt_f32_e32 v227, v227
	v_sqrt_f32_e32 v228, v228
	v_sqrt_f32_e32 v229, v229
	v_sqrt_f32_e32 v230, v230
	v_sqrt_f32_e32 v231, v231
	v_pk_mul_f32 v[224:225], v[224:225], v[64:65]
	v_pk_mul_f32 v[226:227], v[226:227], v[66:67]
	v_pk_mul_f32 v[228:229], v[228:229], v[56:57]
	v_pk_mul_f32 v[230:231], v[230:231], v[58:59]
	v_cvt_pk_bf16_f32 v64, v68, v224
	v_cvt_pk_bf16_f32 v65, v69, v225
	v_cvt_pk_bf16_f32 v66, v70, v226
	v_cvt_pk_bf16_f32 v67, v71, v227
	v_cvt_pk_bf16_f32 v56, v60, v228
	v_cvt_pk_bf16_f32 v57, v61, v229
	v_cvt_pk_bf16_f32 v58, v62, v230
	v_cvt_pk_bf16_f32 v59, v63, v231
	s_add_u32 s98, s98, 0x4000
	s_addc_u32 s99, s99, 0
	global_load_dwordx4 v[248:251], v240, s[98:99]
	v_pk_fma_f32 v[52:53], v[52:53], v[222:223], v[204:205] op_sel_hi:[1,0,1]
	v_pk_fma_f32 v[54:55], v[54:55], v[222:223], v[206:207] op_sel_hi:[1,0,1]
	v_pk_fma_f32 v[32:33], v[32:33], v[222:223], v[208:209] op_sel_hi:[1,0,1]
	v_pk_fma_f32 v[34:35], v[34:35], v[222:223], v[210:211] op_sel_hi:[1,0,1]
	v_pk_fma_f32 v[48:49], v[48:49], v[222:223], v[212:213] op_sel_hi:[1,0,1]
	v_pk_fma_f32 v[50:51], v[50:51], v[222:223], v[214:215] op_sel_hi:[1,0,1]
	v_pk_fma_f32 v[28:29], v[28:29], v[222:223], v[216:217] op_sel_hi:[1,0,1]
	v_pk_fma_f32 v[30:31], v[30:31], v[222:223], v[218:219] op_sel_hi:[1,0,1]
	v_exp_f32_e32 v52, v52
	v_exp_f32_e32 v53, v53
	v_exp_f32_e32 v54, v54
	v_exp_f32_e32 v55, v55
	v_exp_f32_e32 v32, v32
	v_exp_f32_e32 v33, v33
	v_exp_f32_e32 v34, v34
	v_exp_f32_e32 v35, v35
	v_exp_f32_e32 v48, v48
	v_exp_f32_e32 v49, v49
	v_exp_f32_e32 v50, v50
	v_exp_f32_e32 v51, v51
	v_exp_f32_e32 v28, v28
	v_exp_f32_e32 v29, v29
	v_exp_f32_e32 v30, v30
	v_exp_f32_e32 v31, v31
	v_pk_add_f32 v[52:53], v[52:53], v[194:195] op_sel_hi:[1,0]
	v_pk_add_f32 v[54:55], v[54:55], v[194:195] op_sel_hi:[1,0]
	v_pk_add_f32 v[32:33], v[32:33], v[194:195] op_sel_hi:[1,0]
	v_pk_add_f32 v[34:35], v[34:35], v[194:195] op_sel_hi:[1,0]
	v_pk_add_f32 v[48:49], v[48:49], v[194:195] op_sel_hi:[1,0]
	v_pk_add_f32 v[50:51], v[50:51], v[194:195] op_sel_hi:[1,0]
	v_pk_add_f32 v[28:29], v[28:29], v[194:195] op_sel_hi:[1,0]
	v_pk_add_f32 v[30:31], v[30:31], v[194:195] op_sel_hi:[1,0]
	v_rcp_f32_e32 v52, v52
	v_rcp_f32_e32 v53, v53
	v_rcp_f32_e32 v54, v54
	v_rcp_f32_e32 v55, v55
	v_rcp_f32_e32 v32, v32
	v_rcp_f32_e32 v33, v33
	v_rcp_f32_e32 v34, v34
	v_rcp_f32_e32 v35, v35
	v_rcp_f32_e32 v48, v48
	v_rcp_f32_e32 v49, v49
	v_rcp_f32_e32 v50, v50
	v_rcp_f32_e32 v51, v51
	v_rcp_f32_e32 v28, v28
	v_rcp_f32_e32 v29, v29
	v_rcp_f32_e32 v30, v30
	v_rcp_f32_e32 v31, v31
	v_pk_mul_f32 v[52:53], v[52:53], v[196:197]
	v_pk_mul_f32 v[54:55], v[54:55], v[198:199]
	v_pk_mul_f32 v[32:33], v[32:33], v[200:201]
	v_pk_mul_f32 v[34:35], v[34:35], v[202:203]
	v_exp_f32_e32 v52, v52
	v_exp_f32_e32 v53, v53
	v_exp_f32_e32 v54, v54
	v_exp_f32_e32 v55, v55
	v_exp_f32_e32 v32, v32
	v_exp_f32_e32 v33, v33
	v_exp_f32_e32 v34, v34
	v_exp_f32_e32 v35, v35
	s_waitcnt vmcnt(1)
; __device__ __forceinline__ unsigned cvt_pk_bf16(float lo, float hi) { unsigned r; asm volatile("v_cvt_pk_bf16_f32 %0, %1, %2" : "=v"(r) : "v"(lo), "v"(hi)); return r; }
; __device__ __forceinline__ float sigmoidf_(float x) { return 1.f / (1.f + __expf(-x)); }
; __device__ __forceinline__ f32x4 bf4lo(u32x4 r) { return (f32x4){__uint_as_float(r.x << 16), __uint_as_float(r.x & 0xffff0000u), __uint_as_float(r.y << 16), __uint_as_float(r.y & 0xffff0000u)}; }
; __device__ __forceinline__ f32x4 bf4hi(u32x4 r) { return (f32x4){__uint_as_float(r.z << 16), __uint_as_float(r.z & 0xffff0000u), __uint_as_float(r.w << 16), __uint_as_float(r.w & 0xffff0000u)}; }
;     __device__ __forceinline__ void operator()(const f32x4 (&acc)[2][2][4][2], const Unit& u, int wr, int wc, int fr, int fq) const {
;     ...
;             for (int m = 0; m < 4; ++m) { const u32x4 raw = *(const u32x4*)(UCBp + (size_t)(row0 + ai * 128 + m * 16) * 512 + cb); ucv[m][0] = bf4lo(raw); ucv[m][1] = bf4hi(raw); }
; #pragma unroll
;             for (int m = 0; m < 4; ++m)
; #pragma unroll
;                 for (int n = 0; n < 2; ++n) { const size_t off = (size_t)(row0 + ai * 128 + m * 16) * 512 + cb + 4 * n;
;                     const f32x4 uv = ucv[m][n], sp = n ? sp1 : sp0, rb = n ? rb1 : rb0, ib = n ? ib1 : ib0; u32x4 pk;
; #pragma unroll
;                     for (int j = 0; j < 4; ++j) { const float r = sigmoidf_(acc[ai][0][m][n][j] + rb[j]), ig = sigmoidf_(acc[ai][1][m][n][j] + ib[j]);
;                         const float la = sp[j] * r; const float ae = __expf(la); const float om = 1.f - ae; pk[j] = cvt_pk_bf16(om, sqrtf(om * (1.f + ae)) * ig * uv[j]); }
;                     *(u32x4*)(AX + off) = pk; }
	v_lshlrev_b32_e32 v232, 16, v244
	v_and_b32_e32 v233, 0xffff0000, v244
	v_lshlrev_b32_e32 v234, 16, v245
	v_and_b32_e32 v235, 0xffff0000, v245
	v_lshlrev_b32_e32 v236, 16, v246
	v_and_b32_e32 v237, 0xffff0000, v246
	v_lshlrev_b32_e32 v238, 16, v247
	v_and_b32_e32 v239, 0xffff0000, v247
	v_pk_fma_f32 v[224:225], v[52:53], v[52:53], v[194:195] op_sel_hi:[1,1,0] neg_lo:[1,0,0] neg_hi:[1,0,0]
	v_pk_fma_f32 v[226:227], v[54:55], v[54:55], v[194:195] op_sel_hi:[1,1,0] neg_lo:[1,0,0] neg_hi:[1,0,0]
	v_pk_fma_f32 v[228:229], v[32:33], v[32:33], v[194:195] op_sel_hi:[1,1,0] neg_lo:[1,0,0] neg_hi:[1,0,0]
	v_pk_fma_f32 v[230:231], v[34:35], v[34:35], v[194:195] op_sel_hi:[1,1,0] neg_lo:[1,0,0] neg_hi:[1,0,0]
	v_pk_add_f32 v[52:53], v[194:195], v[52:53] op_sel_hi:[0,1] neg_lo:[0,1] neg_hi:[0,1]
	v_pk_add_f32 v[54:55], v[194:195], v[54:55] op_sel_hi:[0,1] neg_lo:[0,1] neg_hi:[0,1]
	v_pk_add_f32 v[32:33], v[194:195], v[32:33] op_sel_hi:[0,1] neg_lo:[0,1] neg_hi:[0,1]
	v_pk_add_f32 v[34:35], v[194:195], v[34:35] op_sel_hi:[0,1] neg_lo:[0,1] neg_hi:[0,1]
	v_pk_mul_f32 v[48:49], v[48:49], v[232:233]
	v_pk_mul_f32 v[50:51], v[50:51], v[234:235]
	v_pk_mul_f32 v[28:29], v[28:29], v[236:237]
	v_pk_mul_f32 v[30:31], v[30:31], v[238:239]
	v_sqrt_f32_e32 v224, v224
	v_sqrt_f32_e32 v225, v225
	v_sqrt_f32_e32 v226, v226
	v_sqrt_f32_e32 v227, v227
	v_sqrt_f32_e32 v228, v228
	v_sqrt_f32_e32 v229, v229
	v_sqrt_f32_e32 v230, v230
	v_sqrt_f32_e32 v231, v231
	v_pk_mul_f32 v[224:225], v[224:225], v[48:49]
	v_pk_mul_f32 v[226:227], v[226:227], v[50:51]
	v_pk_mul_f32 v[228:229], v[228:229], v[28:29]
	v_pk_mul_f32 v[230:231], v[230:231], v[30:31]
	v_cvt_pk_bf16_f32 v48, v52, v224
	v_cvt_pk_bf16_f32 v49, v53, v225
	v_cvt_pk_bf16_f32 v50, v54, v226
	v_cvt_pk_bf16_f32 v51, v55, v227
	v_cvt_pk_bf16_f32 v28, v32, v228
	v_cvt_pk_bf16_f32 v29, v33, v229
	v_cvt_pk_bf16_f32 v30, v34, v230
	v_cvt_pk_bf16_f32 v31, v35, v231
	v_pk_fma_f32 v[12:13], v[12:13], v[222:223], v[204:205] op_sel_hi:[1,0,1]
	v_pk_fma_f32 v[14:15], v[14:15], v[222:223], v[206:207] op_sel_hi:[1,0,1]
	v_pk_fma_f32 v[4:5], v[4:5], v[222:223], v[208:209] op_sel_hi:[1,0,1]
	v_pk_fma_f32 v[6:7], v[6:7], v[222:223], v[210:211] op_sel_hi:[1,0,1]
	v_pk_fma_f32 v[8:9], v[8:9], v[222:223], v[212:213] op_sel_hi:[1,0,1]
	v_pk_fma_f32 v[10:11], v[10:11], v[222:223], v[214:215] op_sel_hi:[1,0,1]
	v_pk_fma_f32 v[0:1], v[0:1], v[222:223], v[216:217] op_sel_hi:[1,0,1]
	v_pk_fma_f32 v[2:3], v[2:3], v[222:223], v[218:219] op_sel_hi:[1,0,1]
	v_exp_f32_e32 v12, v12
	v_exp_f32_e32 v13, v13
	v_exp_f32_e32 v14, v14
	v_exp_f32_e32 v15, v15
	v_exp_f32_e32 v4, v4
	v_exp_f32_e32 v5, v5
	v_exp_f32_e32 v6, v6
	v_exp_f32_e32 v7, v7
	v_exp_f32_e32 v8, v8
	v_exp_f32_e32 v9, v9
	v_exp_f32_e32 v10, v10
	v_exp_f32_e32 v11, v11
	v_exp_f32_e32 v0, v0
	v_exp_f32_e32 v1, v1
	v_exp_f32_e32 v2, v2
	v_exp_f32_e32 v3, v3
	v_pk_add_f32 v[12:13], v[12:13], v[194:195] op_sel_hi:[1,0]
	v_pk_add_f32 v[14:15], v[14:15], v[194:195] op_sel_hi:[1,0]
	v_pk_add_f32 v[4:5], v[4:5], v[194:195] op_sel_hi:[1,0]
	v_pk_add_f32 v[6:7], v[6:7], v[194:195] op_sel_hi:[1,0]
	v_pk_add_f32 v[8:9], v[8:9], v[194:195] op_sel_hi:[1,0]
	v_pk_add_f32 v[10:11], v[10:11], v[194:195] op_sel_hi:[1,0]
	v_pk_add_f32 v[0:1], v[0:1], v[194:195] op_sel_hi:[1,0]
	v_pk_add_f32 v[2:3], v[2:3], v[194:195] op_sel_hi:[1,0]
	v_rcp_f32_e32 v12, v12
	v_rcp_f32_e32 v13, v13
	v_rcp_f32_e32 v14, v14
	v_rcp_f32_e32 v15, v15
	v_rcp_f32_e32 v4, v4
	v_rcp_f32_e32 v5, v5
	v_rcp_f32_e32 v6, v6
	v_rcp_f32_e32 v7, v7
	v_rcp_f32_e32 v8, v8
	v_rcp_f32_e32 v9, v9
	v_rcp_f32_e32 v10, v10
	v_rcp_f32_e32 v11, v11
	v_rcp_f32_e32 v0, v0
	v_rcp_f32_e32 v1, v1
	v_rcp_f32_e32 v2, v2
	v_rcp_f32_e32 v3, v3
	v_pk_mul_f32 v[12:13], v[12:13], v[196:197]
	v_pk_mul_f32 v[14:15], v[14:15], v[198:199]
	v_pk_mul_f32 v[4:5], v[4:5], v[200:201]
	v_pk_mul_f32 v[6:7], v[6:7], v[202:203]
	v_exp_f32_e32 v12, v12
	v_exp_f32_e32 v13, v13
	v_exp_f32_e32 v14, v14
	v_exp_f32_e32 v15, v15
	v_exp_f32_e32 v4, v4
	v_exp_f32_e32 v5, v5
	v_exp_f32_e32 v6, v6
	v_exp_f32_e32 v7, v7
	s_waitcnt vmcnt(0)
; __device__ __forceinline__ unsigned cvt_pk_bf16(float lo, float hi) { unsigned r; asm volatile("v_cvt_pk_bf16_f32 %0, %1, %2" : "=v"(r) : "v"(lo), "v"(hi)); return r; }
; __device__ __forceinline__ float sigmoidf_(float x) { return 1.f / (1.f + __expf(-x)); }
; __device__ __forceinline__ f32x4 bf4lo(u32x4 r) { return (f32x4){__uint_as_float(r.x << 16), __uint_as_float(r.x & 0xffff0000u), __uint_as_float(r.y << 16), __uint_as_float(r.y & 0xffff0000u)}; }
; __device__ __forceinline__ f32x4 bf4hi(u32x4 r) { return (f32x4){__uint_as_float(r.z << 16), __uint_as_float(r.z & 0xffff0000u), __uint_as_float(r.w << 16), __uint_as_float(r.w & 0xffff0000u)}; }
;     __device__ __forceinline__ void operator()(const f32x4 (&acc)[2][2][4][2], const Unit& u, int wr, int wc, int fr, int fq) const {
;     ...
;             for (int m = 0; m < 4; ++m) { const u32x4 raw = *(const u32x4*)(UCBp + (size_t)(row0 + ai * 128 + m * 16) * 512 + cb); ucv[m][0] = bf4lo(raw); ucv[m][1] = bf4hi(raw); }
; #pragma unroll
;             for (int m = 0; m < 4; ++m)
; #pragma unroll
;                 for (int n = 0; n < 2; ++n) { const size_t off = (size_t)(row0 + ai * 128 + m * 16) * 512 + cb + 4 * n;
;                     const f32x4 uv = ucv[m][n], sp = n ? sp1 : sp0, rb = n ? rb1 : rb0, ib = n ? ib1 : ib0; u32x4 pk;
; #pragma unroll
;                     for (int j = 0; j < 4; ++j) { const float r = sigmoidf_(acc[ai][0][m][n][j] + rb[j]), ig = sigmoidf_(acc[ai][1][m][n][j] + ib[j]);
;                         const float la = sp[j] * r; const float ae = __expf(la); const float om = 1.f - ae; pk[j] = cvt_pk_bf16(om, sqrtf(om * (1.f + ae)) * ig * uv[j]); }
;                     *(u32x4*)(AX + off) = pk; }
	v_lshlrev_b32_e32 v232, 16, v248
	v_and_b32_e32 v233, 0xffff0000, v248
	v_lshlrev_b32_e32 v234, 16, v249
	v_and_b32_e32 v235, 0xffff0000, v249
	v_lshlrev_b32_e32 v236, 16, v250
	v_and_b32_e32 v237, 0xffff0000, v250
	v_lshlrev_b32_e32 v238, 16, v251
	v_and_b32_e32 v239, 0xffff0000, v251
	v_pk_fma_f32 v[224:225], v[12:13], v[12:13], v[194:195] op_sel_hi:[1,1,0] neg_lo:[1,0,0] neg_hi:[1,0,0]
	v_pk_fma_f32 v[226:227], v[14:15], v[14:15], v[194:195] op_sel_hi:[1,1,0] neg_lo:[1,0,0] neg_hi:[1,0,0]
	v_pk_fma_f32 v[228:229], v[4:5], v[4:5], v[194:195] op_sel_hi:[1,1,0] neg_lo:[1,0,0] neg_hi:[1,0,0]
	v_pk_fma_f32 v[230:231], v[6:7], v[6:7], v[194:195] op_sel_hi:[1,1,0] neg_lo:[1,0,0] neg_hi:[1,0,0]
	v_pk_add_f32 v[12:13], v[194:195], v[12:13] op_sel_hi:[0,1] neg_lo:[0,1] neg_hi:[0,1]
	v_pk_add_f32 v[14:15], v[194:195], v[14:15] op_sel_hi:[0,1] neg_lo:[0,1] neg_hi:[0,1]
	v_pk_add_f32 v[4:5], v[194:195], v[4:5] op_sel_hi:[0,1] neg_lo:[0,1] neg_hi:[0,1]
	v_pk_add_f32 v[6:7], v[194:195], v[6:7] op_sel_hi:[0,1] neg_lo:[0,1] neg_hi:[0,1]
	v_pk_mul_f32 v[8:9], v[8:9], v[232:233]
	v_pk_mul_f32 v[10:11], v[10:11], v[234:235]
	v_pk_mul_f32 v[0:1], v[0:1], v[236:237]
	v_pk_mul_f32 v[2:3], v[2:3], v[238:239]
	v_sqrt_f32_e32 v224, v224
	v_sqrt_f32_e32 v225, v225
	v_sqrt_f32_e32 v226, v226
	v_sqrt_f32_e32 v227, v227
	v_sqrt_f32_e32 v228, v228
	v_sqrt_f32_e32 v229, v229
	v_sqrt_f32_e32 v230, v230
	v_sqrt_f32_e32 v231, v231
	v_pk_mul_f32 v[224:225], v[224:225], v[8:9]
	v_pk_mul_f32 v[226:227], v[226:227], v[10:11]
	v_pk_mul_f32 v[228:229], v[228:229], v[0:1]
	v_pk_mul_f32 v[230:231], v[230:231], v[2:3]
	v_cvt_pk_bf16_f32 v8, v12, v224
	v_cvt_pk_bf16_f32 v9, v13, v225
	v_cvt_pk_bf16_f32 v10, v14, v226
	v_cvt_pk_bf16_f32 v11, v15, v227
	v_cvt_pk_bf16_f32 v0, v4, v228
	v_cvt_pk_bf16_f32 v1, v5, v229
	v_cvt_pk_bf16_f32 v2, v6, v230
	v_cvt_pk_bf16_f32 v3, v7, v231
	global_store_dwordx4 v242, v[144:147], s[100:101]
	global_store_dwordx4 v242, v[136:139], s[100:101] offset:16
	s_add_u32 s100, s100, 0x8000
	s_addc_u32 s101, s101, 0
	global_store_dwordx4 v242, v[128:131], s[100:101]
	global_store_dwordx4 v242, v[120:123], s[100:101] offset:16
	s_add_u32 s100, s100, 0x8000
	s_addc_u32 s101, s101, 0
	global_store_dwordx4 v242, v[112:115], s[100:101]
	global_store_dwordx4 v242, v[104:107], s[100:101] offset:16
	s_add_u32 s100, s100, 0x8000
	s_addc_u32 s101, s101, 0
	global_store_dwordx4 v242, v[96:99], s[100:101]
	global_store_dwordx4 v242, v[88:91], s[100:101] offset:16
	s_add_u32 s100, s100, 0x28000
	s_addc_u32 s101, s101, 0
	global_store_dwordx4 v242, v[80:83], s[100:101]
	global_store_dwordx4 v242, v[72:75], s[100:101] offset:16
	s_add_u32 s100, s100, 0x8000
	s_addc_u32 s101, s101, 0
	global_store_dwordx4 v242, v[64:67], s[100:101]
	global_store_dwordx4 v242, v[56:59], s[100:101] offset:16
	s_add_u32 s100, s100, 0x8000
	s_addc_u32 s101, s101, 0
	global_store_dwordx4 v242, v[48:51], s[100:101]
	global_store_dwordx4 v242, v[28:31], s[100:101] offset:16
	s_add_u32 s100, s100, 0x8000
	s_addc_u32 s101, s101, 0
	global_store_dwordx4 v242, v[8:11], s[100:101]
	global_store_dwordx4 v242, v[0:3], s[100:101] offset:16
	s_mov_b64 s[0:1], -1
	s_and_b64 vcc, exec, s[2:3]
	s_cbranch_vccnz .LBB0_549
	s_andn2_b64 vcc, exec, s[8:9]
	s_cbranch_vccnz .LBB0_548
	s_barrier
	s_branch .LBB0_548
